# DSA unit prologue: the selection-mask blocks fetched with back-to-back loads and one wait (was load/wait-all/ds_write per block)
# speedup vs baseline: 1.0120x; 1.0022x over previous
;   #define DMA_K(t,slot) glds16(ksrc+(long)(t)*KVBLK*KP,(unsigned)__builtin_amdgcn_readfirstlane(kdst+(slot)))
;   #define DMA_V(t,slot) glds16(vsrc+(long)(t)*KVBLK*VP,(unsigned)__builtin_amdgcn_readfirstlane(vdst+(slot)))
;     ...
;   const bf16*ksrc=Kh+(long)lane*KP+wid*8;
;   const bf16*vsrc=Vh+(long)(16*(wid&3)+(lane>>2))*VP+(wid>>2)*32+(lane&3)*8;
;   const unsigned kdst=lds0+LDS_K+wid*1024, vdst=lds0+LDS_V+wid*1024;
;     ...
;   const int vb0=(int)(lds0+LDS_V)+((lane>>4)&1)*32+(lane&3)*8+(4*hi+((lane&15)>>2))*64;
;   const char*Kbase=shm+LDS_K; bf16x8 kf[8];
;   const lds_cptr shm3=(lds_cptr)shm; const lds_cptr kp0=shm3+LDS_K+hi*1024+r32*16; const lds_cptr vp0=shm3+LDS_V+((lane>>4)&1)*32+(lane&3)*8+(4*hi+((lane&15)>>2))*64;
;   const int NT=(q0+QB)/KVBLK;
;   const __attribute__((address_space(3))) unsigned* mimg=(const __attribute__((address_space(3))) unsigned*)(shm3+LDS_OST+wid*MWAVE)+r32;
;   DMA_K(0,0);DMA_V(0,0);DMA_K(1,SLOTB);
;   if constexpr(MASKED){
;     __attribute__((address_space(3))) u32x4* mdst=(__attribute__((address_space(3))) u32x4*)(shm3+LDS_OST+wid*MWAVE)+lane;
;     for(int i=0;i<=qb;++i){ const u32x4 v=((const u32x4*)mwave)[i*64+lane]; mdst[i*64]=v; }
;   }
.LBB0_1512:
	s_and_b64 vcc, exec, s[0:1]
	s_cbranch_vccz .LBB0_1379
	s_lshl_b64 s[0:1], s[30:31], 18
	s_add_u32 s2, s56, s0
	s_addc_u32 s3, s57, s1
	s_add_u32 s22, s58, s0
	s_addc_u32 s23, s59, s1
	s_lshl_b32 s1, s79, 3
	s_lshl_b32 s0, s30, 6
	s_add_i32 s1, s1, s93
	s_add_i32 s8, s1, s0
	s_lshl_b64 s[0:1], s[8:9], 13
	v_mbcnt_lo_u32_b32 v42, -1, 0
	v_mbcnt_hi_u32_b32 v42, -1, v42
	s_add_u32 s4, s68, s0
	v_add_u32_e32 v0, s70, v42
	v_and_b32_e32 v46, 63, v42
	v_readfirstlane_b32 s0, v0
	s_addc_u32 s5, s69, s1
	s_ashr_i32 s1, s0, 6
	v_lshlrev_b32_e32 v0, 7, v46
	v_lshl_add_u64 v[2:3], s[2:3], 0, v[0:1]
	s_lshl_b32 s2, s1, 3
	s_ashr_i32 s3, s2, 31
	v_lshl_add_u64 v[44:45], s[2:3], 1, v[2:3]
	s_lshl_b32 s2, s1, 4
	v_bfe_u32 v0, v42, 2, 4
	v_and_or_b32 v0, s2, 48, v0
	s_ashr_i32 s2, s0, 3
	s_andn2_b32 s2, s2, 31
	v_lshlrev_b32_e32 v0, 7, v0
	s_ashr_i32 s3, s2, 31
	s_lshl_b32 s48, s1, 10
	v_lshl_add_u64 v[2:3], s[22:23], 0, v[0:1]
	v_lshlrev_b32_e32 v214, 3, v42
	s_cmp_lg_u32 0, -1
	v_lshl_add_u64 v[2:3], s[2:3], 1, v[2:3]
	v_and_b32_e32 v219, 24, v214
	s_cselect_b32 s2, 0, 0
	v_lshlrev_b32_e32 v0, 1, v219
	s_add_i32 s48, s48, s2
	s_mov_b32 s2, m0
	s_mov_b32 m0, s48
	s_nop 0
	global_load_lds_dwordx4 v[44:45], off
	s_mov_b32 m0, s2
	v_lshl_add_u64 v[40:41], v[2:3], 0, v[0:1]
	s_add_i32 s49, s48, 0x6000
	s_mov_b32 s2, m0
	s_mov_b32 m0, s49
	s_nop 0
	global_load_lds_dwordx4 v[40:41], off
	s_mov_b32 m0, s2
	v_lshl_add_u64 v[2:3], v[44:45], 0, s[18:19]
	s_add_i32 s2, s48, 0x2000
	s_mov_b32 s3, m0
	s_mov_b32 m0, s2
	s_nop 0
	global_load_lds_dwordx4 v[2:3], off
	s_mov_b32 m0, s3
	v_lshlrev_b32_e32 v0, 4, v46
	s_lshl_b32 s36, s1, 13
	s_add_i32 s46, s36, 0
	v_add_u32_e32 v4, s46, v0
	v_add_u32_e32 v132, 0x1000, v0
	global_load_dwordx4 v[100:103], v0, s[4:5]
	s_cmp_lt_u32 s79, 1
	s_cbranch_scc1 .Ldm_wait
	global_load_dwordx4 v[104:107], v0, s[4:5] offset:1024
	s_cmp_lt_u32 s79, 2
	s_cbranch_scc1 .Ldm_wait
	global_load_dwordx4 v[108:111], v0, s[4:5] offset:2048
	s_cmp_lt_u32 s79, 3
	s_cbranch_scc1 .Ldm_wait
	global_load_dwordx4 v[112:115], v0, s[4:5] offset:3072
	s_cmp_lt_u32 s79, 4
	s_cbranch_scc1 .Ldm_wait
	global_load_dwordx4 v[116:119], v132, s[4:5]
	s_cmp_lt_u32 s79, 5
	s_cbranch_scc1 .Ldm_wait
	global_load_dwordx4 v[120:123], v132, s[4:5] offset:1024
	s_cmp_lt_u32 s79, 6
	s_cbranch_scc1 .Ldm_wait
	global_load_dwordx4 v[124:127], v132, s[4:5] offset:2048
	s_cmp_lt_u32 s79, 7
	s_cbranch_scc1 .Ldm_wait
	global_load_dwordx4 v[128:131], v132, s[4:5] offset:3072
.Ldm_wait:
	s_cmp_lg_u32 s79, 0
	s_cselect_b64 s[2:3], -1, 0
	s_waitcnt vmcnt(0)
	ds_write_b128 v4, v[100:103] offset:51200
	s_cmp_lt_u32 s79, 1
	s_cbranch_scc1 .LBB0_1521
	ds_write_b128 v4, v[104:107] offset:52224
	s_cmp_lt_u32 s79, 2
	s_cbranch_scc1 .LBB0_1521
	ds_write_b128 v4, v[108:111] offset:53248
	s_cmp_lt_u32 s79, 3
	s_cbranch_scc1 .LBB0_1521
	ds_write_b128 v4, v[112:115] offset:54272
	s_cmp_lt_u32 s79, 4
	s_cbranch_scc1 .LBB0_1521
	ds_write_b128 v4, v[116:119] offset:55296
	s_cmp_lt_u32 s79, 5
	s_cbranch_scc1 .LBB0_1521
	ds_write_b128 v4, v[120:123] offset:56320
	s_cmp_lt_u32 s79, 6
	s_cbranch_scc1 .LBB0_1521
	ds_write_b128 v4, v[124:127] offset:57344
	s_cmp_lt_u32 s79, 7
	s_cbranch_scc1 .LBB0_1521
	ds_write_b128 v4, v[128:131] offset:58368
